# QKV-type instance: write-through (sc1) output stores
# baseline (speedup 1.0000x reference)
; __device__ __forceinline__ unsigned cvt_pk_bf16(float lo, float hi) { unsigned r; asm volatile("v_cvt_pk_bf16_f32 %0, %1, %2" : "=v"(r) : "v"(lo), "v"(hi)); return r; }
; __device__ __forceinline__ float gelu_tanh(float x) { const float u = 0.7978845608028654f * (x + 0.044715f * x * x * x); return x * fast_rcp(1.0f + fast_exp2(-2.0f * LOG2E * u)); }
; #define PG8_STAGE(bufoff, gbase, voff) do { _Pragma("unroll") for (int _i = 0; _i < 2; ++_i) \
;         __builtin_amdgcn_global_load_lds((const unsigned*)((const char*)(gbase) + (voff)[_i]), (LAS unsigned*)(lds + (bufoff) + ldsw + _i * 8192), 16, 0, 0); } while (0)
; #define PG8_LDA(dst, b, h) do { _Pragma("unroll") for (int m = 0; m < 4; ++m) _Pragma("unroll") for (int k = 0; k < 2; ++k) dst[m][k] = *(const LAS bf16x8*)(lds + PG8_SA(b, h) + aoff + m * 2048 + k * 1024); } while (0)
; #define PG8_LDB(dst, b, h) do { _Pragma("unroll") for (int n = 0; n < 2; ++n) _Pragma("unroll") for (int k = 0; k < 2; ++k) dst[n][k] = *(const LAS bf16x8*)(lds + PG8_SB(b, h) + boff + n * 2048 + k * 1024); } while (0)
; #define PG8_WAIT_V(n) asm volatile("s_waitcnt vmcnt(" #n ")" ::: "memory")
;     __device__ __forceinline__ void operator()(const f32x4 (&acc)[2][2][4][2], const Unit& u, int wr, int wc, int fr, int fq) const {
;     ...
;             for (int m = 0; m < 4; ++m) { const int row = row0 + ai * HALF + m * 16; bf16_t* rowp = O + (size_t)row * ldc + col0; const float rs = rsv[ai][m];
; #pragma unroll
;                 for (int bj = 0; bj < 2; ++bj) { f32x4 v0 = acc[ai][bj][m][0] * rs, v1 = acc[ai][bj][m][1] * rs;
;                     if (ACT == 1) {
; #pragma unroll
;                         for (int j = 0; j < 4; ++j) { v0[j] = gelu_tanh(v0[j]); v1[j] = gelu_tanh(v1[j]); } }
;                     u32x4 w; w.x = cvt_pk_bf16(v0[0], v0[1]); w.y = cvt_pk_bf16(v0[2], v0[3]); w.z = cvt_pk_bf16(v1[0], v1[1]); w.w = cvt_pk_bf16(v1[2], v1[3]);
;                     *(u32x4*)(rowp + bj * HALF) = w; } }
; template <class Epi, bool ALIGN_EPI>
; __device__ __forceinline__ void gemm_phase(LAS unsigned char* lds, const Gemm g, const StaticOrder& S, const Epi& E, const int tid) {
;     ...
;             PG8_LDB(B0, 0, 0); PG8_LDB(B1, 0, 1); PG8_SCHED; PG8_LDA(At, 0, 0); PG8_STAGE(PG8_SA(1, 1), a1 + hA, voffA);
;             PG8_WAIT_V(8); PG8_WAIT_L(0); PG8_BAR; PG8_MMA(0, 0, At, B0); PG8_MMA(0, 1, At, B1); PG8_BAR; PG8_SCHED;
.Lq5_first_epi:
	s_add_i32 s11, s10, 2
	s_cmp_eq_u32 s55, s10
	s_cselect_b64 vcc, -1, 0
	v_add_u32_e32 v148, s33, v149
	s_add_i32 s10, 0, 0x14000
	ds_read_b128 v[152:155], v148
	ds_read_b128 v[156:159], v148 offset:1024
	ds_read_b128 v[160:163], v148 offset:2048
	ds_read_b128 v[164:167], v148 offset:3072
	v_add_u32_e32 v148, s10, v149
	ds_read_b128 v[176:179], v148
	ds_read_b128 v[180:183], v148 offset:1024
	ds_read_b128 v[184:187], v148 offset:2048
	ds_read_b128 v[188:191], v148 offset:3072
	v_lshl_add_u64 v[146:147], v[142:143], 0, s[92:93]
	v_cndmask_b32_e32 v147, v147, v139, vcc
	v_cndmask_b32_e32 v146, v146, v138, vcc
	v_cndmask_b32_e32 v221, v145, v141, vcc
	v_cndmask_b32_e32 v220, v144, v140, vcc
	v_lshl_add_u64 v[244:245], v[142:143], 0, v[134:135]
	s_add_i32 m0, s25, 0xc000
	ds_read_b128 v[192:195], v151
	ds_read_b128 v[196:199], v151 offset:1024
	ds_read_b128 v[200:203], v151 offset:2048
	ds_read_b128 v[204:207], v151 offset:3072
	ds_read_b128 v[208:211], v151 offset:4096
	ds_read_b128 v[212:215], v151 offset:5120
	ds_read_b128 v[216:219], v151 offset:6144
	ds_read_b128 v[240:243], v151 offset:7168
	global_load_lds_dwordx4 v[244:245], off
	v_lshl_add_u64 v[244:245], v[142:143], 0, v[136:137]
	s_add_i32 m0, s25, 0xe000
	s_nop 0
	global_load_lds_dwordx4 v[244:245], off
	s_waitcnt vmcnt(16)
	s_waitcnt lgkmcnt(0)
	s_barrier
	s_setprio 1
	s_waitcnt lgkmcnt(0)
	v_mfma_f32_16x16x32_bf16 v[124:127], v[152:155], v[192:195], 0
	s_lshl_b32 s98, s28, 5
	s_mov_b32 s99, 0
	v_mul_f32_e32 v60, v238, v60
	v_mul_f32_e32 v61, v238, v61
	v_mfma_f32_16x16x32_bf16 v[120:123], v[160:163], v[192:195], 0
	v_mul_f32_e32 v62, v238, v62
	v_mul_f32_e32 v63, v238, v63
	v_mul_f32_e32 v56, v238, v56
	v_mul_f32_e32 v57, v238, v57
	v_mfma_f32_16x16x32_bf16 v[108:111], v[152:155], v[200:203], 0
	v_mul_f32_e32 v58, v238, v58
	v_mul_f32_e32 v59, v238, v59
	v_cvt_pk_bf16_f32 v60, v60, v61
	v_cvt_pk_bf16_f32 v61, v62, v63
	v_mfma_f32_16x16x32_bf16 v[104:107], v[160:163], v[200:203], 0
	v_cvt_pk_bf16_f32 v62, v56, v57
	v_cvt_pk_bf16_f32 v63, v58, v59
	global_store_dwordx4 v[232:233], v[60:63], off sc1
	v_mul_f32_e32 v52, v238, v52
	v_mfma_f32_16x16x32_bf16 v[92:95], v[152:155], v[208:211], 0
	v_mul_f32_e32 v53, v238, v53
	v_mul_f32_e32 v54, v238, v54
	v_mul_f32_e32 v55, v238, v55
	v_mul_f32_e32 v48, v238, v48
	v_mfma_f32_16x16x32_bf16 v[88:91], v[160:163], v[208:211], 0
	v_mul_f32_e32 v49, v238, v49
	v_mul_f32_e32 v50, v238, v50
	v_mul_f32_e32 v51, v238, v51
	v_cvt_pk_bf16_f32 v52, v52, v53
	v_mfma_f32_16x16x32_bf16 v[76:79], v[152:155], v[216:219], 0
	v_cvt_pk_bf16_f32 v53, v54, v55
	v_cvt_pk_bf16_f32 v54, v48, v49
	v_cvt_pk_bf16_f32 v55, v50, v51
	global_store_dwordx4 v[232:233], v[52:55], off offset:256 sc1
	v_mfma_f32_16x16x32_bf16 v[72:75], v[160:163], v[216:219], 0
	v_lshl_add_u64 v[232:233], v[232:233], 0, s[98:99]
	v_mul_f32_e32 v44, v239, v44
	v_mul_f32_e32 v45, v239, v45
	v_mul_f32_e32 v46, v239, v46
	v_mfma_f32_16x16x32_bf16 v[124:127], v[156:159], v[196:199], v[124:127]
	v_mul_f32_e32 v47, v239, v47
	v_mul_f32_e32 v40, v239, v40
	v_mul_f32_e32 v41, v239, v41
	v_mul_f32_e32 v42, v239, v42
	v_mfma_f32_16x16x32_bf16 v[120:123], v[164:167], v[196:199], v[120:123]
	v_mul_f32_e32 v43, v239, v43
	v_cvt_pk_bf16_f32 v44, v44, v45
	v_cvt_pk_bf16_f32 v45, v46, v47
	v_cvt_pk_bf16_f32 v46, v40, v41
	v_mfma_f32_16x16x32_bf16 v[108:111], v[156:159], v[204:207], v[108:111]
	v_cvt_pk_bf16_f32 v47, v42, v43
	global_store_dwordx4 v[232:233], v[44:47], off sc1
	v_mul_f32_e32 v36, v239, v36
	v_mul_f32_e32 v37, v239, v37
	v_mfma_f32_16x16x32_bf16 v[104:107], v[164:167], v[204:207], v[104:107]
	v_mul_f32_e32 v38, v239, v38
	v_mul_f32_e32 v39, v239, v39
	v_mul_f32_e32 v32, v239, v32
	v_mul_f32_e32 v33, v239, v33
	v_mfma_f32_16x16x32_bf16 v[92:95], v[156:159], v[212:215], v[92:95]
	v_mul_f32_e32 v34, v239, v34
	v_mul_f32_e32 v35, v239, v35
	v_cvt_pk_bf16_f32 v36, v36, v37
	v_cvt_pk_bf16_f32 v37, v38, v39
	v_mfma_f32_16x16x32_bf16 v[88:91], v[164:167], v[212:215], v[88:91]
	v_cvt_pk_bf16_f32 v38, v32, v33
	v_cvt_pk_bf16_f32 v39, v34, v35
	global_store_dwordx4 v[232:233], v[36:39], off offset:256 sc1
	v_lshl_add_u64 v[232:233], v[232:233], 0, s[98:99]
	v_mfma_f32_16x16x32_bf16 v[76:79], v[156:159], v[240:243], v[76:79]
	v_mul_f32_e32 v28, v230, v28
	v_mul_f32_e32 v29, v230, v29
	v_mul_f32_e32 v30, v230, v30
	v_mul_f32_e32 v31, v230, v31
	v_mfma_f32_16x16x32_bf16 v[72:75], v[164:167], v[240:243], v[72:75]
	v_mul_f32_e32 v24, v230, v24
	v_mul_f32_e32 v25, v230, v25
	v_mul_f32_e32 v26, v230, v26
	v_mul_f32_e32 v27, v230, v27
	s_setprio 0
	s_setprio 1
	v_mfma_f32_16x16x32_bf16 v[116:119], v[176:179], v[192:195], 0
	v_cvt_pk_bf16_f32 v28, v28, v29
	v_cvt_pk_bf16_f32 v29, v30, v31
	v_cvt_pk_bf16_f32 v30, v24, v25
	v_cvt_pk_bf16_f32 v31, v26, v27
	v_mfma_f32_16x16x32_bf16 v[112:115], v[184:187], v[192:195], 0
	global_store_dwordx4 v[232:233], v[28:31], off sc1
	v_mul_f32_e32 v20, v230, v20
	v_mul_f32_e32 v21, v230, v21
	v_mul_f32_e32 v22, v230, v22
	v_mfma_f32_16x16x32_bf16 v[100:103], v[176:179], v[200:203], 0
	v_mul_f32_e32 v23, v230, v23
	v_mul_f32_e32 v16, v230, v16
	v_mul_f32_e32 v17, v230, v17
	v_mul_f32_e32 v18, v230, v18
	v_mfma_f32_16x16x32_bf16 v[96:99], v[184:187], v[200:203], 0
	v_mul_f32_e32 v19, v230, v19
	v_cvt_pk_bf16_f32 v20, v20, v21
	v_cvt_pk_bf16_f32 v21, v22, v23
	v_cvt_pk_bf16_f32 v22, v16, v17
	v_mfma_f32_16x16x32_bf16 v[84:87], v[176:179], v[208:211], 0
	v_cvt_pk_bf16_f32 v23, v18, v19
	global_store_dwordx4 v[232:233], v[20:23], off offset:256 sc1
	v_lshl_add_u64 v[232:233], v[232:233], 0, s[98:99]
	v_mul_f32_e32 v12, v231, v12
	v_mfma_f32_16x16x32_bf16 v[80:83], v[184:187], v[208:211], 0
; #define PG8_STAGE(bufoff, gbase, voff) do { _Pragma("unroll") for (int _i = 0; _i < 2; ++_i) \
;         __builtin_amdgcn_global_load_lds((const unsigned*)((const char*)(gbase) + (voff)[_i]), (LAS unsigned*)(lds + (bufoff) + ldsw + _i * 8192), 16, 0, 0); } while (0)
; #define PG8_LDA(dst, b, h) do { _Pragma("unroll") for (int m = 0; m < 4; ++m) _Pragma("unroll") for (int k = 0; k < 2; ++k) dst[m][k] = *(const LAS bf16x8*)(lds + PG8_SA(b, h) + aoff + m * 2048 + k * 1024); } while (0)
; #define PG8_LDB(dst, b, h) do { _Pragma("unroll") for (int n = 0; n < 2; ++n) _Pragma("unroll") for (int k = 0; k < 2; ++k) dst[n][k] = *(const LAS bf16x8*)(lds + PG8_SB(b, h) + boff + n * 2048 + k * 1024); } while (0)
; #define PG8_MMA(ai, bj, At, Bt) do { __builtin_amdgcn_s_setprio(1); _Pragma("unroll") for (int k = 0; k < 2; ++k) _Pragma("unroll") for (int m = 0; m < 4; ++m) _Pragma("unroll") for (int n = 0; n < 2; ++n) \
;         acc[ai][bj][m][n] = __builtin_amdgcn_mfma_f32_16x16x32_bf16(Bt[n][k], At[m][k], acc[ai][bj][m][n], 0, 0, 0); __builtin_amdgcn_s_setprio(0); } while (0)
; #define PG8_WAIT_V(n) asm volatile("s_waitcnt vmcnt(" #n ")" ::: "memory")
; #define PG8_WAIT_L(n) asm volatile("s_waitcnt lgkmcnt(" #n ")" ::: "memory")
; #define PG8_BAR __builtin_amdgcn_s_barrier()
; template <class Epi, bool ALIGN_EPI>
; __device__ __forceinline__ void gemm_phase(LAS unsigned char* lds, const Gemm g, const StaticOrder& S, const Epi& E, const int tid) {
;     ...
;             PG8_WAIT_V(8); PG8_WAIT_L(0); PG8_BAR; PG8_MMA(0, 0, At, B0); PG8_MMA(0, 1, At, B1); PG8_BAR; PG8_SCHED;
;             PG8_LDA(At, 0, 1); PG8_STAGE(PG8_SB(0, 0), b2, voffB); PG8_STAGE(PG8_SB(0, 1), b2 + hB, voffB); PG8_STAGE(PG8_SA(0, 0), a2, voffA);
;             PG8_WAIT_V(8); PG8_WAIT_L(0); PG8_BAR; PG8_MMA(1, 0, At, B0); PG8_MMA(1, 1, At, B1); PG8_BAR; PG8_SCHED;
;             PG8_LDB(B0, 1, 0); PG8_LDB(B1, 1, 1); PG8_SCHED; PG8_LDA(At, 1, 0); PG8_STAGE(PG8_SA(0, 1), a2 + hA, voffA);
;             PG8_WAIT_V(8); PG8_WAIT_L(0); PG8_BAR; PG8_MMA(0, 0, At, B0); PG8_MMA(0, 1, At, B1); PG8_BAR; PG8_SCHED;
;             PG8_LDA(At, 1, 1); PG8_STAGE(PG8_SB(1, 0), b3, voffB); PG8_STAGE(PG8_SB(1, 1), b3 + hB, voffB); PG8_STAGE(PG8_SA(1, 0), a3, voffA);
;             PG8_WAIT_V(8); PG8_WAIT_L(0); PG8_BAR; PG8_MMA(1, 0, At, B0); PG8_MMA(1, 1, At, B1); PG8_BAR; PG8_SCHED;
	v_mul_f32_e32 v13, v231, v13
	v_mul_f32_e32 v14, v231, v14
	v_mul_f32_e32 v15, v231, v15
	v_mul_f32_e32 v8, v231, v8
	v_mfma_f32_16x16x32_bf16 v[68:71], v[176:179], v[216:219], 0
	v_mul_f32_e32 v9, v231, v9
	v_mul_f32_e32 v10, v231, v10
	v_mul_f32_e32 v11, v231, v11
	v_cvt_pk_bf16_f32 v12, v12, v13
	v_mfma_f32_16x16x32_bf16 v[64:67], v[184:187], v[216:219], 0
	v_cvt_pk_bf16_f32 v13, v14, v15
	v_cvt_pk_bf16_f32 v14, v8, v9
	v_cvt_pk_bf16_f32 v15, v10, v11
	global_store_dwordx4 v[232:233], v[12:15], off sc1
	v_mfma_f32_16x16x32_bf16 v[116:119], v[180:183], v[196:199], v[116:119]
	v_mul_f32_e32 v4, v231, v4
	v_mul_f32_e32 v5, v231, v5
	v_mul_f32_e32 v6, v231, v6
	v_mul_f32_e32 v7, v231, v7
	v_mfma_f32_16x16x32_bf16 v[112:115], v[188:191], v[196:199], v[112:115]
	v_mul_f32_e32 v0, v231, v0
	v_mul_f32_e32 v1, v231, v1
	v_mul_f32_e32 v2, v231, v2
	v_mul_f32_e32 v3, v231, v3
	v_mfma_f32_16x16x32_bf16 v[100:103], v[180:183], v[204:207], v[100:103]
	v_cvt_pk_bf16_f32 v4, v4, v5
	v_cvt_pk_bf16_f32 v5, v6, v7
	v_cvt_pk_bf16_f32 v6, v0, v1
	v_cvt_pk_bf16_f32 v7, v2, v3
	v_mfma_f32_16x16x32_bf16 v[96:99], v[188:191], v[204:207], v[96:99]
	global_store_dwordx4 v[232:233], v[4:7], off offset:256 sc1
	v_mfma_f32_16x16x32_bf16 v[84:87], v[180:183], v[212:215], v[84:87]
	v_mfma_f32_16x16x32_bf16 v[80:83], v[188:191], v[212:215], v[80:83]
	v_mfma_f32_16x16x32_bf16 v[68:71], v[180:183], v[240:243], v[68:71]
	v_mfma_f32_16x16x32_bf16 v[64:67], v[188:191], v[240:243], v[64:67]
	s_setprio 0
	s_barrier
	s_add_i32 s62, s33, s45
	v_lshl_add_u64 v[244:245], v[220:221], 0, v[168:169]
	s_mov_b32 m0, s62
	ds_read_b128 v[192:195], v151 offset:16384
	ds_read_b128 v[196:199], v151 offset:17408
	ds_read_b128 v[200:203], v151 offset:18432
	ds_read_b128 v[204:207], v151 offset:19456
	ds_read_b128 v[208:211], v151 offset:20480
	ds_read_b128 v[212:215], v151 offset:21504
	ds_read_b128 v[216:219], v151 offset:22528
	ds_read_b128 v[240:243], v151 offset:23552
	global_load_lds_dwordx4 v[244:245], off
	v_lshl_add_u64 v[246:247], v[220:221], 0, v[128:129]
	s_add_i32 m0, s62, 0x2000
	v_lshl_add_u64 v[220:221], v[220:221], 0, s[12:13]
	s_add_i32 s10, s10, s45
	global_load_lds_dwordx4 v[246:247], off
	v_lshl_add_u64 v[248:249], v[220:221], 0, v[168:169]
	s_mov_b32 m0, s10
	v_lshl_add_u64 v[220:221], v[220:221], 0, v[128:129]
	global_load_lds_dwordx4 v[248:249], off
	s_add_i32 m0, s10, 0x2000
	v_lshl_add_u64 v[250:251], v[146:147], 0, v[132:133]
	global_load_lds_dwordx4 v[220:221], off
	s_mov_b32 m0, s25
	v_lshl_add_u64 v[252:253], v[146:147], 0, v[130:131]
	global_load_lds_dwordx4 v[250:251], off
	s_mov_b32 m0, s50
	s_nop 0
	global_load_lds_dwordx4 v[252:253], off
	s_waitcnt vmcnt(24)
	s_waitcnt lgkmcnt(0)
	s_barrier
	s_setprio 1
	s_waitcnt lgkmcnt(0)
	v_mfma_f32_16x16x32_bf16 v[60:63], v[152:155], v[192:195], 0
	v_mfma_f32_16x16x32_bf16 v[56:59], v[160:163], v[192:195], 0
	v_mfma_f32_16x16x32_bf16 v[44:47], v[152:155], v[200:203], 0
	v_mfma_f32_16x16x32_bf16 v[40:43], v[160:163], v[200:203], 0
	v_mfma_f32_16x16x32_bf16 v[28:31], v[152:155], v[208:211], 0
	v_mfma_f32_16x16x32_bf16 v[24:27], v[160:163], v[208:211], 0
	v_mfma_f32_16x16x32_bf16 v[12:15], v[152:155], v[216:219], 0
	v_mfma_f32_16x16x32_bf16 v[8:11], v[160:163], v[216:219], 0
	v_mfma_f32_16x16x32_bf16 v[60:63], v[156:159], v[196:199], v[60:63]
	v_mfma_f32_16x16x32_bf16 v[56:59], v[164:167], v[196:199], v[56:59]
	v_mfma_f32_16x16x32_bf16 v[44:47], v[156:159], v[204:207], v[44:47]
	v_mfma_f32_16x16x32_bf16 v[40:43], v[164:167], v[204:207], v[40:43]
	v_mfma_f32_16x16x32_bf16 v[28:31], v[156:159], v[212:215], v[28:31]
	v_mfma_f32_16x16x32_bf16 v[24:27], v[164:167], v[212:215], v[24:27]
	v_mfma_f32_16x16x32_bf16 v[12:15], v[156:159], v[240:243], v[12:15]
	v_mfma_f32_16x16x32_bf16 v[8:11], v[164:167], v[240:243], v[8:11]
	s_setprio 0
	s_setprio 1
	v_mfma_f32_16x16x32_bf16 v[52:55], v[176:179], v[192:195], 0
	v_mfma_f32_16x16x32_bf16 v[48:51], v[184:187], v[192:195], 0
	v_mfma_f32_16x16x32_bf16 v[36:39], v[176:179], v[200:203], 0
	v_mfma_f32_16x16x32_bf16 v[32:35], v[184:187], v[200:203], 0
	v_mfma_f32_16x16x32_bf16 v[20:23], v[176:179], v[208:211], 0
	v_mfma_f32_16x16x32_bf16 v[16:19], v[184:187], v[208:211], 0
	v_mfma_f32_16x16x32_bf16 v[4:7], v[176:179], v[216:219], 0
	v_mfma_f32_16x16x32_bf16 v[0:3], v[184:187], v[216:219], 0
	v_mfma_f32_16x16x32_bf16 v[52:55], v[180:183], v[196:199], v[52:55]
	v_mfma_f32_16x16x32_bf16 v[48:51], v[188:191], v[196:199], v[48:51]
	v_mfma_f32_16x16x32_bf16 v[36:39], v[180:183], v[204:207], v[36:39]
	v_mfma_f32_16x16x32_bf16 v[32:35], v[188:191], v[204:207], v[32:35]
	v_mfma_f32_16x16x32_bf16 v[20:23], v[180:183], v[212:215], v[20:23]
	v_mfma_f32_16x16x32_bf16 v[16:19], v[188:191], v[212:215], v[16:19]
	v_mfma_f32_16x16x32_bf16 v[4:7], v[180:183], v[240:243], v[4:7]
	v_mfma_f32_16x16x32_bf16 v[0:3], v[188:191], v[240:243], v[0:3]
	s_setprio 0
	s_barrier
	s_add_i32 s10, 0, 0x18000
	v_add_u32_e32 v148, s10, v149
	s_add_i32 s62, 0, 0x1c000
	ds_read_b128 v[152:155], v148
	ds_read_b128 v[156:159], v148 offset:1024
	ds_read_b128 v[160:163], v148 offset:2048
	ds_read_b128 v[164:167], v148 offset:3072
	v_add_u32_e32 v148, s62, v149
	ds_read_b128 v[176:179], v148
	ds_read_b128 v[180:183], v148 offset:1024
	ds_read_b128 v[184:187], v148 offset:2048
	ds_read_b128 v[188:191], v148 offset:3072
	v_lshl_add_u64 v[146:147], v[146:147], 0, s[94:95]
	s_mov_b32 m0, s51
	v_lshl_add_u64 v[226:227], v[146:147], 0, v[132:133]
	ds_read_b128 v[192:195], v151 offset:32768
	ds_read_b128 v[196:199], v151 offset:33792
	ds_read_b128 v[200:203], v151 offset:34816
	ds_read_b128 v[204:207], v151 offset:35840
	ds_read_b128 v[208:211], v151 offset:36864
	ds_read_b128 v[212:215], v151 offset:37888
	ds_read_b128 v[216:219], v151 offset:38912
	ds_read_b128 v[240:243], v151 offset:39936
	global_load_lds_dwordx4 v[226:227], off
	v_lshl_add_u64 v[146:147], v[146:147], 0, v[130:131]
	s_mov_b32 m0, s52
	s_nop 0
	global_load_lds_dwordx4 v[146:147], off
	s_waitcnt vmcnt(16)
	s_waitcnt lgkmcnt(0)
	s_barrier
; #define PG8_STAGE(bufoff, gbase, voff) do { _Pragma("unroll") for (int _i = 0; _i < 2; ++_i) \
;         __builtin_amdgcn_global_load_lds((const unsigned*)((const char*)(gbase) + (voff)[_i]), (LAS unsigned*)(lds + (bufoff) + ldsw + _i * 8192), 16, 0, 0); } while (0)
; #define PG8_LDA(dst, b, h) do { _Pragma("unroll") for (int m = 0; m < 4; ++m) _Pragma("unroll") for (int k = 0; k < 2; ++k) dst[m][k] = *(const LAS bf16x8*)(lds + PG8_SA(b, h) + aoff + m * 2048 + k * 1024); } while (0)
; #define PG8_LDB(dst, b, h) do { _Pragma("unroll") for (int n = 0; n < 2; ++n) _Pragma("unroll") for (int k = 0; k < 2; ++k) dst[n][k] = *(const LAS bf16x8*)(lds + PG8_SB(b, h) + boff + n * 2048 + k * 1024); } while (0)
; #define PG8_MMA(ai, bj, At, Bt) do { __builtin_amdgcn_s_setprio(1); _Pragma("unroll") for (int k = 0; k < 2; ++k) _Pragma("unroll") for (int m = 0; m < 4; ++m) _Pragma("unroll") for (int n = 0; n < 2; ++n) \
;         acc[ai][bj][m][n] = __builtin_amdgcn_mfma_f32_16x16x32_bf16(Bt[n][k], At[m][k], acc[ai][bj][m][n], 0, 0, 0); __builtin_amdgcn_s_setprio(0); } while (0)
; #define PG8_WAIT_V(n) asm volatile("s_waitcnt vmcnt(" #n ")" ::: "memory")
; #define PG8_WAIT_L(n) asm volatile("s_waitcnt lgkmcnt(" #n ")" ::: "memory")
; #define PG8_BAR __builtin_amdgcn_s_barrier()
; #define PG8_SCHED __builtin_amdgcn_sched_barrier(0)
; template <class Epi, bool ALIGN_EPI>
; __device__ __forceinline__ void gemm_phase(LAS unsigned char* lds, const Gemm g, const StaticOrder& S, const Epi& E, const int tid) {
;     ...
;             PG8_WAIT_V(8); PG8_WAIT_L(0); PG8_BAR; PG8_MMA(1, 0, At, B0); PG8_MMA(1, 1, At, B1); PG8_BAR; PG8_SCHED;
;             PG8_LDB(B0, 1, 0); PG8_LDB(B1, 1, 1); PG8_SCHED; PG8_LDA(At, 1, 0); PG8_STAGE(PG8_SA(0, 1), a2 + hA, voffA);
;             PG8_WAIT_V(8); PG8_WAIT_L(0); PG8_BAR; PG8_MMA(0, 0, At, B0); PG8_MMA(0, 1, At, B1); PG8_BAR; PG8_SCHED;
;             PG8_LDA(At, 1, 1); PG8_STAGE(PG8_SB(1, 0), b3, voffB); PG8_STAGE(PG8_SB(1, 1), b3 + hB, voffB); PG8_STAGE(PG8_SA(1, 0), a3, voffA);
;             PG8_WAIT_V(8); PG8_WAIT_L(0); PG8_BAR; PG8_MMA(1, 0, At, B0); PG8_MMA(1, 1, At, B1); PG8_BAR; PG8_SCHED;
;         }
	s_setprio 1
	s_waitcnt lgkmcnt(0)
	v_mfma_f32_16x16x32_bf16 v[124:127], v[152:155], v[192:195], v[124:127]
	v_mfma_f32_16x16x32_bf16 v[120:123], v[160:163], v[192:195], v[120:123]
	v_mfma_f32_16x16x32_bf16 v[108:111], v[152:155], v[200:203], v[108:111]
	v_mfma_f32_16x16x32_bf16 v[104:107], v[160:163], v[200:203], v[104:107]
	v_mfma_f32_16x16x32_bf16 v[92:95], v[152:155], v[208:211], v[92:95]
	v_mfma_f32_16x16x32_bf16 v[88:91], v[160:163], v[208:211], v[88:91]
	v_mfma_f32_16x16x32_bf16 v[76:79], v[152:155], v[216:219], v[76:79]
	v_mfma_f32_16x16x32_bf16 v[72:75], v[160:163], v[216:219], v[72:75]
	v_mfma_f32_16x16x32_bf16 v[124:127], v[156:159], v[196:199], v[124:127]
	v_mfma_f32_16x16x32_bf16 v[120:123], v[164:167], v[196:199], v[120:123]
	v_mfma_f32_16x16x32_bf16 v[108:111], v[156:159], v[204:207], v[108:111]
	v_mfma_f32_16x16x32_bf16 v[104:107], v[164:167], v[204:207], v[104:107]
	v_mfma_f32_16x16x32_bf16 v[92:95], v[156:159], v[212:215], v[92:95]
	v_mfma_f32_16x16x32_bf16 v[88:91], v[164:167], v[212:215], v[88:91]
	v_mfma_f32_16x16x32_bf16 v[76:79], v[156:159], v[240:243], v[76:79]
	v_mfma_f32_16x16x32_bf16 v[72:75], v[164:167], v[240:243], v[72:75]
	s_setprio 0
	s_setprio 1
	v_mfma_f32_16x16x32_bf16 v[116:119], v[176:179], v[192:195], v[116:119]
	v_mfma_f32_16x16x32_bf16 v[112:115], v[184:187], v[192:195], v[112:115]
	v_mfma_f32_16x16x32_bf16 v[100:103], v[176:179], v[200:203], v[100:103]
	v_mfma_f32_16x16x32_bf16 v[96:99], v[184:187], v[200:203], v[96:99]
	v_mfma_f32_16x16x32_bf16 v[84:87], v[176:179], v[208:211], v[84:87]
	v_mfma_f32_16x16x32_bf16 v[80:83], v[184:187], v[208:211], v[80:83]
	v_mfma_f32_16x16x32_bf16 v[68:71], v[176:179], v[216:219], v[68:71]
	v_mfma_f32_16x16x32_bf16 v[64:67], v[184:187], v[216:219], v[64:67]
	v_mfma_f32_16x16x32_bf16 v[116:119], v[180:183], v[196:199], v[116:119]
	v_mfma_f32_16x16x32_bf16 v[112:115], v[188:191], v[196:199], v[112:115]
	v_mfma_f32_16x16x32_bf16 v[100:103], v[180:183], v[204:207], v[100:103]
	v_mfma_f32_16x16x32_bf16 v[96:99], v[188:191], v[204:207], v[96:99]
	v_mfma_f32_16x16x32_bf16 v[84:87], v[180:183], v[212:215], v[84:87]
	v_mfma_f32_16x16x32_bf16 v[80:83], v[188:191], v[212:215], v[80:83]
	v_mfma_f32_16x16x32_bf16 v[68:71], v[180:183], v[240:243], v[68:71]
	v_mfma_f32_16x16x32_bf16 v[64:67], v[188:191], v[240:243], v[64:67]
	s_setprio 0
	s_barrier
	s_add_i32 s10, s10, s45
	v_lshl_add_u64 v[146:147], v[244:245], 0, s[92:93]
	s_mov_b32 m0, s10
	ds_read_b128 v[192:195], v151 offset:49152
	ds_read_b128 v[196:199], v151 offset:50176
	ds_read_b128 v[200:203], v151 offset:51200
	ds_read_b128 v[204:207], v151 offset:52224
	ds_read_b128 v[208:211], v151 offset:53248
	ds_read_b128 v[212:215], v151 offset:54272
	ds_read_b128 v[216:219], v151 offset:55296
	ds_read_b128 v[240:243], v151 offset:56320
	global_load_lds_dwordx4 v[146:147], off
	v_lshl_add_u64 v[146:147], v[246:247], 0, s[92:93]
	s_add_i32 m0, s10, 0x2000
	s_add_i32 s10, s62, s45
	global_load_lds_dwordx4 v[146:147], off
	v_lshl_add_u64 v[146:147], v[248:249], 0, s[92:93]
	s_mov_b32 m0, s10
	s_nop 0
	global_load_lds_dwordx4 v[146:147], off
	v_lshl_add_u64 v[146:147], v[220:221], 0, s[92:93]
	s_add_i32 m0, s10, 0x2000
	s_nop 0
	global_load_lds_dwordx4 v[146:147], off
	v_lshl_add_u64 v[146:147], v[250:251], 0, s[92:93]
	s_mov_b32 m0, s53
	s_nop 0
	global_load_lds_dwordx4 v[146:147], off
	v_lshl_add_u64 v[146:147], v[252:253], 0, s[92:93]
	s_mov_b32 m0, s54
	s_nop 0
	global_load_lds_dwordx4 v[146:147], off
	s_waitcnt vmcnt(8)
	s_waitcnt lgkmcnt(0)
	s_barrier
	s_setprio 1
	s_waitcnt lgkmcnt(0)
	v_mfma_f32_16x16x32_bf16 v[60:63], v[152:155], v[192:195], v[60:63]
	v_mfma_f32_16x16x32_bf16 v[56:59], v[160:163], v[192:195], v[56:59]
	v_mfma_f32_16x16x32_bf16 v[44:47], v[152:155], v[200:203], v[44:47]
	v_mfma_f32_16x16x32_bf16 v[40:43], v[160:163], v[200:203], v[40:43]
	v_mfma_f32_16x16x32_bf16 v[28:31], v[152:155], v[208:211], v[28:31]
	v_mfma_f32_16x16x32_bf16 v[24:27], v[160:163], v[208:211], v[24:27]
	v_mfma_f32_16x16x32_bf16 v[12:15], v[152:155], v[216:219], v[12:15]
	v_mfma_f32_16x16x32_bf16 v[8:11], v[160:163], v[216:219], v[8:11]
	v_mfma_f32_16x16x32_bf16 v[60:63], v[156:159], v[196:199], v[60:63]
	v_mfma_f32_16x16x32_bf16 v[56:59], v[164:167], v[196:199], v[56:59]
	v_mfma_f32_16x16x32_bf16 v[44:47], v[156:159], v[204:207], v[44:47]
	v_mfma_f32_16x16x32_bf16 v[40:43], v[164:167], v[204:207], v[40:43]
	v_mfma_f32_16x16x32_bf16 v[28:31], v[156:159], v[212:215], v[28:31]
	v_mfma_f32_16x16x32_bf16 v[24:27], v[164:167], v[212:215], v[24:27]
	v_mfma_f32_16x16x32_bf16 v[12:15], v[156:159], v[240:243], v[12:15]
	v_mfma_f32_16x16x32_bf16 v[8:11], v[164:167], v[240:243], v[8:11]
	s_setprio 0
	s_setprio 1
	v_mfma_f32_16x16x32_bf16 v[52:55], v[176:179], v[192:195], v[52:55]
	v_mfma_f32_16x16x32_bf16 v[48:51], v[184:187], v[192:195], v[48:51]
	v_mfma_f32_16x16x32_bf16 v[36:39], v[176:179], v[200:203], v[36:39]
	v_mfma_f32_16x16x32_bf16 v[32:35], v[184:187], v[200:203], v[32:35]
	v_mfma_f32_16x16x32_bf16 v[20:23], v[176:179], v[208:211], v[20:23]
	v_mfma_f32_16x16x32_bf16 v[16:19], v[184:187], v[208:211], v[16:19]
	v_mfma_f32_16x16x32_bf16 v[4:7], v[176:179], v[216:219], v[4:7]
	v_mfma_f32_16x16x32_bf16 v[0:3], v[184:187], v[216:219], v[0:3]
	v_mfma_f32_16x16x32_bf16 v[52:55], v[180:183], v[196:199], v[52:55]
	v_mfma_f32_16x16x32_bf16 v[48:51], v[188:191], v[196:199], v[48:51]
	v_mfma_f32_16x16x32_bf16 v[36:39], v[180:183], v[204:207], v[36:39]
	v_mfma_f32_16x16x32_bf16 v[32:35], v[188:191], v[204:207], v[32:35]
	v_mfma_f32_16x16x32_bf16 v[20:23], v[180:183], v[212:215], v[20:23]
	v_mfma_f32_16x16x32_bf16 v[16:19], v[188:191], v[212:215], v[16:19]
	v_mfma_f32_16x16x32_bf16 v[4:7], v[180:183], v[240:243], v[4:7]
	v_mfma_f32_16x16x32_bf16 v[0:3], v[188:191], v[240:243], v[0:3]
	s_setprio 0
	s_barrier
	v_lshl_add_u64 v[142:143], v[142:143], 0, s[80:81]
	v_lshl_add_u64 v[144:145], v[144:145], 0, s[80:81]
	s_mov_b32 s10, s11
	s_cmp_eq_u32 s10, s55
	s_cbranch_scc1 .Lq5_last
	s_branch .LBB0_354

; #define PG8_STAGE(bufoff, gbase, voff) do { _Pragma("unroll") for (int _i = 0; _i < 2; ++_i) \
;         __builtin_amdgcn_global_load_lds((const unsigned*)((const char*)(gbase) + (voff)[_i]), (LAS unsigned*)(lds + (bufoff) + ldsw + _i * 8192), 16, 0, 0); } while (0)
; #define PG8_LDA(dst, b, h) do { _Pragma("unroll") for (int m = 0; m < 4; ++m) _Pragma("unroll") for (int k = 0; k < 2; ++k) dst[m][k] = *(const LAS bf16x8*)(lds + PG8_SA(b, h) + aoff + m * 2048 + k * 1024); } while (0)
; #define PG8_LDB(dst, b, h) do { _Pragma("unroll") for (int n = 0; n < 2; ++n) _Pragma("unroll") for (int k = 0; k < 2; ++k) dst[n][k] = *(const LAS bf16x8*)(lds + PG8_SB(b, h) + boff + n * 2048 + k * 1024); } while (0)
; #define PG8_MMA(ai, bj, At, Bt) do { __builtin_amdgcn_s_setprio(1); _Pragma("unroll") for (int k = 0; k < 2; ++k) _Pragma("unroll") for (int m = 0; m < 4; ++m) _Pragma("unroll") for (int n = 0; n < 2; ++n) \
;         acc[ai][bj][m][n] = __builtin_amdgcn_mfma_f32_16x16x32_bf16(Bt[n][k], At[m][k], acc[ai][bj][m][n], 0, 0, 0); __builtin_amdgcn_s_setprio(0); } while (0)
; template <class Epi, bool ALIGN_EPI>
; __device__ __forceinline__ void gemm_phase(LAS unsigned char* lds, const Gemm g, const StaticOrder& S, const Epi& E, const int tid) {
;     ...
;         for (int t = 0; t < nt; t += 2) {
;             const bool last = (t == nt - 2);
;             const char* a1 = cA + (size_t)(t + 1) * kstep;
;             const char* a2 = last ? nA : cA + (size_t)(t + 2) * kstep; const char* b2 = last ? nB : cB + (size_t)(t + 2) * kstep;
;             const char* a3 = a2 + kstep; const char* b3 = b2 + kstep;
;             PG8_LDB(B0, 0, 0); PG8_LDB(B1, 0, 1); PG8_SCHED; PG8_LDA(At, 0, 0); PG8_STAGE(PG8_SA(1, 1), a1 + hA, voffA);
;             PG8_WAIT_V(8); PG8_WAIT_L(0); PG8_BAR; PG8_MMA(0, 0, At, B0); PG8_MMA(0, 1, At, B1); PG8_BAR; PG8_SCHED;
;             PG8_LDA(At, 0, 1); PG8_STAGE(PG8_SB(0, 0), b2, voffB); PG8_STAGE(PG8_SB(0, 1), b2 + hB, voffB); PG8_STAGE(PG8_SA(0, 0), a2, voffA);
;             PG8_WAIT_V(8); PG8_WAIT_L(0); PG8_BAR; PG8_MMA(1, 0, At, B0); PG8_MMA(1, 1, At, B1); PG8_BAR; PG8_SCHED;
;             PG8_LDB(B0, 1, 0); PG8_LDB(B1, 1, 1); PG8_SCHED; PG8_LDA(At, 1, 0); PG8_STAGE(PG8_SA(0, 1), a2 + hA, voffA);
;             PG8_WAIT_V(8); PG8_WAIT_L(0); PG8_BAR; PG8_MMA(0, 0, At, B0); PG8_MMA(0, 1, At, B1); PG8_BAR; PG8_SCHED;
.Lq5_last:
	s_add_i32 s11, s10, 2
	s_cmp_eq_u32 s55, s10
	s_cselect_b64 vcc, -1, 0
	v_add_u32_e32 v148, s33, v149
	s_add_i32 s10, 0, 0x14000
	ds_read_b128 v[152:155], v148
	ds_read_b128 v[156:159], v148 offset:1024
	ds_read_b128 v[160:163], v148 offset:2048
	ds_read_b128 v[164:167], v148 offset:3072
	v_add_u32_e32 v148, s10, v149
	ds_read_b128 v[176:179], v148
	ds_read_b128 v[180:183], v148 offset:1024
	ds_read_b128 v[184:187], v148 offset:2048
	ds_read_b128 v[188:191], v148 offset:3072
	v_lshl_add_u64 v[146:147], v[142:143], 0, s[92:93]
	v_cndmask_b32_e32 v147, v147, v139, vcc
	v_cndmask_b32_e32 v146, v146, v138, vcc
	v_cndmask_b32_e32 v221, v145, v141, vcc
	v_cndmask_b32_e32 v220, v144, v140, vcc
	v_lshl_add_u64 v[244:245], v[142:143], 0, v[134:135]
	s_add_i32 m0, s25, 0xc000
	ds_read_b128 v[192:195], v151
	ds_read_b128 v[196:199], v151 offset:1024
	ds_read_b128 v[200:203], v151 offset:2048
	ds_read_b128 v[204:207], v151 offset:3072
	ds_read_b128 v[208:211], v151 offset:4096
	ds_read_b128 v[212:215], v151 offset:5120
	ds_read_b128 v[216:219], v151 offset:6144
	ds_read_b128 v[240:243], v151 offset:7168
	global_load_lds_dwordx4 v[244:245], off
	v_lshl_add_u64 v[244:245], v[142:143], 0, v[136:137]
	s_add_i32 m0, s25, 0xe000
	s_nop 0
	global_load_lds_dwordx4 v[244:245], off
	s_waitcnt vmcnt(8)
	s_waitcnt lgkmcnt(0)
	s_barrier
	s_setprio 1
	s_waitcnt lgkmcnt(0)
	v_mfma_f32_16x16x32_bf16 v[124:127], v[152:155], v[192:195], v[124:127]
	v_mfma_f32_16x16x32_bf16 v[120:123], v[160:163], v[192:195], v[120:123]
	v_mfma_f32_16x16x32_bf16 v[108:111], v[152:155], v[200:203], v[108:111]
	v_mfma_f32_16x16x32_bf16 v[104:107], v[160:163], v[200:203], v[104:107]
	v_mfma_f32_16x16x32_bf16 v[92:95], v[152:155], v[208:211], v[92:95]
	v_mfma_f32_16x16x32_bf16 v[88:91], v[160:163], v[208:211], v[88:91]
	v_mfma_f32_16x16x32_bf16 v[76:79], v[152:155], v[216:219], v[76:79]
	v_mfma_f32_16x16x32_bf16 v[72:75], v[160:163], v[216:219], v[72:75]
	v_mfma_f32_16x16x32_bf16 v[124:127], v[156:159], v[196:199], v[124:127]
	v_mfma_f32_16x16x32_bf16 v[120:123], v[164:167], v[196:199], v[120:123]
	v_mfma_f32_16x16x32_bf16 v[108:111], v[156:159], v[204:207], v[108:111]
	v_mfma_f32_16x16x32_bf16 v[104:107], v[164:167], v[204:207], v[104:107]
	v_mfma_f32_16x16x32_bf16 v[92:95], v[156:159], v[212:215], v[92:95]
	v_mfma_f32_16x16x32_bf16 v[88:91], v[164:167], v[212:215], v[88:91]
	v_mfma_f32_16x16x32_bf16 v[76:79], v[156:159], v[240:243], v[76:79]
	v_mfma_f32_16x16x32_bf16 v[72:75], v[164:167], v[240:243], v[72:75]
	s_setprio 0
	s_setprio 1
	v_mfma_f32_16x16x32_bf16 v[116:119], v[176:179], v[192:195], v[116:119]
	v_mfma_f32_16x16x32_bf16 v[112:115], v[184:187], v[192:195], v[112:115]
	v_mfma_f32_16x16x32_bf16 v[100:103], v[176:179], v[200:203], v[100:103]
	v_mfma_f32_16x16x32_bf16 v[96:99], v[184:187], v[200:203], v[96:99]
	v_mfma_f32_16x16x32_bf16 v[84:87], v[176:179], v[208:211], v[84:87]
	v_mfma_f32_16x16x32_bf16 v[80:83], v[184:187], v[208:211], v[80:83]
	v_mfma_f32_16x16x32_bf16 v[68:71], v[176:179], v[216:219], v[68:71]
	v_mfma_f32_16x16x32_bf16 v[64:67], v[184:187], v[216:219], v[64:67]
	v_mfma_f32_16x16x32_bf16 v[116:119], v[180:183], v[196:199], v[116:119]
	v_mfma_f32_16x16x32_bf16 v[112:115], v[188:191], v[196:199], v[112:115]
	v_mfma_f32_16x16x32_bf16 v[100:103], v[180:183], v[204:207], v[100:103]
	v_mfma_f32_16x16x32_bf16 v[96:99], v[188:191], v[204:207], v[96:99]
	v_mfma_f32_16x16x32_bf16 v[84:87], v[180:183], v[212:215], v[84:87]
	v_mfma_f32_16x16x32_bf16 v[80:83], v[188:191], v[212:215], v[80:83]
	v_mfma_f32_16x16x32_bf16 v[68:71], v[180:183], v[240:243], v[68:71]
	v_mfma_f32_16x16x32_bf16 v[64:67], v[188:191], v[240:243], v[64:67]
	s_setprio 0
	s_barrier
	s_add_i32 s62, s33, s45
	v_lshl_add_u64 v[244:245], v[220:221], 0, v[168:169]
	s_mov_b32 m0, s62
	ds_read_b128 v[192:195], v151 offset:16384
	ds_read_b128 v[196:199], v151 offset:17408
	ds_read_b128 v[200:203], v151 offset:18432
	ds_read_b128 v[204:207], v151 offset:19456
	ds_read_b128 v[208:211], v151 offset:20480
	ds_read_b128 v[212:215], v151 offset:21504
	ds_read_b128 v[216:219], v151 offset:22528
	ds_read_b128 v[240:243], v151 offset:23552
	global_load_lds_dwordx4 v[244:245], off
	v_lshl_add_u64 v[246:247], v[220:221], 0, v[128:129]
	s_add_i32 m0, s62, 0x2000
	v_lshl_add_u64 v[220:221], v[220:221], 0, s[12:13]
	s_add_i32 s10, s10, s45
	global_load_lds_dwordx4 v[246:247], off
	v_lshl_add_u64 v[248:249], v[220:221], 0, v[168:169]
	s_mov_b32 m0, s10
	v_lshl_add_u64 v[220:221], v[220:221], 0, v[128:129]
	global_load_lds_dwordx4 v[248:249], off
	s_add_i32 m0, s10, 0x2000
	v_lshl_add_u64 v[250:251], v[146:147], 0, v[132:133]
	global_load_lds_dwordx4 v[220:221], off
	s_mov_b32 m0, s25
	v_lshl_add_u64 v[252:253], v[146:147], 0, v[130:131]
	global_load_lds_dwordx4 v[250:251], off
	s_mov_b32 m0, s50
	s_nop 0
	global_load_lds_dwordx4 v[252:253], off
	s_waitcnt vmcnt(8)
	s_waitcnt lgkmcnt(0)
	s_barrier
; #define PG8_STAGE(bufoff, gbase, voff) do { _Pragma("unroll") for (int _i = 0; _i < 2; ++_i) \
;         __builtin_amdgcn_global_load_lds((const unsigned*)((const char*)(gbase) + (voff)[_i]), (LAS unsigned*)(lds + (bufoff) + ldsw + _i * 8192), 16, 0, 0); } while (0)
; #define PG8_LDA(dst, b, h) do { _Pragma("unroll") for (int m = 0; m < 4; ++m) _Pragma("unroll") for (int k = 0; k < 2; ++k) dst[m][k] = *(const LAS bf16x8*)(lds + PG8_SA(b, h) + aoff + m * 2048 + k * 1024); } while (0)
; #define PG8_LDB(dst, b, h) do { _Pragma("unroll") for (int n = 0; n < 2; ++n) _Pragma("unroll") for (int k = 0; k < 2; ++k) dst[n][k] = *(const LAS bf16x8*)(lds + PG8_SB(b, h) + boff + n * 2048 + k * 1024); } while (0)
; #define PG8_MMA(ai, bj, At, Bt) do { __builtin_amdgcn_s_setprio(1); _Pragma("unroll") for (int k = 0; k < 2; ++k) _Pragma("unroll") for (int m = 0; m < 4; ++m) _Pragma("unroll") for (int n = 0; n < 2; ++n) \
;         acc[ai][bj][m][n] = __builtin_amdgcn_mfma_f32_16x16x32_bf16(Bt[n][k], At[m][k], acc[ai][bj][m][n], 0, 0, 0); __builtin_amdgcn_s_setprio(0); } while (0)
; #define PG8_WAIT_V(n) asm volatile("s_waitcnt vmcnt(" #n ")" ::: "memory")
; #define PG8_WAIT_L(n) asm volatile("s_waitcnt lgkmcnt(" #n ")" ::: "memory")
; #define PG8_BAR __builtin_amdgcn_s_barrier()
; #define PG8_SCHED __builtin_amdgcn_sched_barrier(0)
; template <class Epi, bool ALIGN_EPI>
; __device__ __forceinline__ void gemm_phase(LAS unsigned char* lds, const Gemm g, const StaticOrder& S, const Epi& E, const int tid) {
;     ...
;             PG8_WAIT_V(8); PG8_WAIT_L(0); PG8_BAR; PG8_MMA(1, 0, At, B0); PG8_MMA(1, 1, At, B1); PG8_BAR; PG8_SCHED;
;             PG8_LDB(B0, 1, 0); PG8_LDB(B1, 1, 1); PG8_SCHED; PG8_LDA(At, 1, 0); PG8_STAGE(PG8_SA(0, 1), a2 + hA, voffA);
;             PG8_WAIT_V(8); PG8_WAIT_L(0); PG8_BAR; PG8_MMA(0, 0, At, B0); PG8_MMA(0, 1, At, B1); PG8_BAR; PG8_SCHED;
;             PG8_LDA(At, 1, 1); PG8_STAGE(PG8_SB(1, 0), b3, voffB); PG8_STAGE(PG8_SB(1, 1), b3 + hB, voffB); PG8_STAGE(PG8_SA(1, 0), a3, voffA);
;             PG8_WAIT_V(8); PG8_WAIT_L(0); PG8_BAR; PG8_MMA(1, 0, At, B0); PG8_MMA(1, 1, At, B1); PG8_BAR; PG8_SCHED;
	s_setprio 1
	s_waitcnt lgkmcnt(0)
	v_mfma_f32_16x16x32_bf16 v[60:63], v[152:155], v[192:195], v[60:63]
	v_mfma_f32_16x16x32_bf16 v[56:59], v[160:163], v[192:195], v[56:59]
	v_mfma_f32_16x16x32_bf16 v[44:47], v[152:155], v[200:203], v[44:47]
	v_mfma_f32_16x16x32_bf16 v[40:43], v[160:163], v[200:203], v[40:43]
	v_mfma_f32_16x16x32_bf16 v[28:31], v[152:155], v[208:211], v[28:31]
	v_mfma_f32_16x16x32_bf16 v[24:27], v[160:163], v[208:211], v[24:27]
	v_mfma_f32_16x16x32_bf16 v[12:15], v[152:155], v[216:219], v[12:15]
	v_mfma_f32_16x16x32_bf16 v[8:11], v[160:163], v[216:219], v[8:11]
	v_mfma_f32_16x16x32_bf16 v[60:63], v[156:159], v[196:199], v[60:63]
	v_mfma_f32_16x16x32_bf16 v[56:59], v[164:167], v[196:199], v[56:59]
	v_mfma_f32_16x16x32_bf16 v[44:47], v[156:159], v[204:207], v[44:47]
	v_mfma_f32_16x16x32_bf16 v[40:43], v[164:167], v[204:207], v[40:43]
	v_mfma_f32_16x16x32_bf16 v[28:31], v[156:159], v[212:215], v[28:31]
	v_mfma_f32_16x16x32_bf16 v[24:27], v[164:167], v[212:215], v[24:27]
	v_mfma_f32_16x16x32_bf16 v[12:15], v[156:159], v[240:243], v[12:15]
	v_mfma_f32_16x16x32_bf16 v[8:11], v[164:167], v[240:243], v[8:11]
	s_setprio 0
	s_setprio 1
	v_mfma_f32_16x16x32_bf16 v[52:55], v[176:179], v[192:195], v[52:55]
	v_mfma_f32_16x16x32_bf16 v[48:51], v[184:187], v[192:195], v[48:51]
	v_mfma_f32_16x16x32_bf16 v[36:39], v[176:179], v[200:203], v[36:39]
	v_mfma_f32_16x16x32_bf16 v[32:35], v[184:187], v[200:203], v[32:35]
	v_mfma_f32_16x16x32_bf16 v[20:23], v[176:179], v[208:211], v[20:23]
	v_mfma_f32_16x16x32_bf16 v[16:19], v[184:187], v[208:211], v[16:19]
	v_mfma_f32_16x16x32_bf16 v[4:7], v[176:179], v[216:219], v[4:7]
	v_mfma_f32_16x16x32_bf16 v[0:3], v[184:187], v[216:219], v[0:3]
	v_mfma_f32_16x16x32_bf16 v[52:55], v[180:183], v[196:199], v[52:55]
	v_mfma_f32_16x16x32_bf16 v[48:51], v[188:191], v[196:199], v[48:51]
	v_mfma_f32_16x16x32_bf16 v[36:39], v[180:183], v[204:207], v[36:39]
	v_mfma_f32_16x16x32_bf16 v[32:35], v[188:191], v[204:207], v[32:35]
	v_mfma_f32_16x16x32_bf16 v[20:23], v[180:183], v[212:215], v[20:23]
	v_mfma_f32_16x16x32_bf16 v[16:19], v[188:191], v[212:215], v[16:19]
	v_mfma_f32_16x16x32_bf16 v[4:7], v[180:183], v[240:243], v[4:7]
	v_mfma_f32_16x16x32_bf16 v[0:3], v[188:191], v[240:243], v[0:3]
	s_setprio 0
	s_barrier
	s_add_i32 s10, 0, 0x18000
	v_add_u32_e32 v148, s10, v149
	s_add_i32 s62, 0, 0x1c000
	ds_read_b128 v[152:155], v148
	ds_read_b128 v[156:159], v148 offset:1024
	ds_read_b128 v[160:163], v148 offset:2048
	ds_read_b128 v[164:167], v148 offset:3072
	v_add_u32_e32 v148, s62, v149
	ds_read_b128 v[176:179], v148
	ds_read_b128 v[180:183], v148 offset:1024
	ds_read_b128 v[184:187], v148 offset:2048
	ds_read_b128 v[188:191], v148 offset:3072
	v_lshl_add_u64 v[146:147], v[146:147], 0, s[94:95]
	s_mov_b32 m0, s51
	v_lshl_add_u64 v[226:227], v[146:147], 0, v[132:133]
	ds_read_b128 v[192:195], v151 offset:32768
	ds_read_b128 v[196:199], v151 offset:33792
	ds_read_b128 v[200:203], v151 offset:34816
	ds_read_b128 v[204:207], v151 offset:35840
	ds_read_b128 v[208:211], v151 offset:36864
	ds_read_b128 v[212:215], v151 offset:37888
	ds_read_b128 v[216:219], v151 offset:38912
	ds_read_b128 v[240:243], v151 offset:39936
	global_load_lds_dwordx4 v[226:227], off
	v_lshl_add_u64 v[146:147], v[146:147], 0, v[130:131]
	s_mov_b32 m0, s52
	s_nop 0
	global_load_lds_dwordx4 v[146:147], off
	s_waitcnt vmcnt(8)
	s_waitcnt lgkmcnt(0)
	s_barrier
	s_setprio 1
	s_waitcnt lgkmcnt(0)
	v_mfma_f32_16x16x32_bf16 v[124:127], v[152:155], v[192:195], v[124:127]
	v_mfma_f32_16x16x32_bf16 v[120:123], v[160:163], v[192:195], v[120:123]
	v_mfma_f32_16x16x32_bf16 v[108:111], v[152:155], v[200:203], v[108:111]
	v_mfma_f32_16x16x32_bf16 v[104:107], v[160:163], v[200:203], v[104:107]
	v_mfma_f32_16x16x32_bf16 v[92:95], v[152:155], v[208:211], v[92:95]
	v_mfma_f32_16x16x32_bf16 v[88:91], v[160:163], v[208:211], v[88:91]
	v_mfma_f32_16x16x32_bf16 v[76:79], v[152:155], v[216:219], v[76:79]
	v_mfma_f32_16x16x32_bf16 v[72:75], v[160:163], v[216:219], v[72:75]
	v_mfma_f32_16x16x32_bf16 v[124:127], v[156:159], v[196:199], v[124:127]
	v_mfma_f32_16x16x32_bf16 v[120:123], v[164:167], v[196:199], v[120:123]
	v_mfma_f32_16x16x32_bf16 v[108:111], v[156:159], v[204:207], v[108:111]
	v_mfma_f32_16x16x32_bf16 v[104:107], v[164:167], v[204:207], v[104:107]
	v_mfma_f32_16x16x32_bf16 v[92:95], v[156:159], v[212:215], v[92:95]
	v_mfma_f32_16x16x32_bf16 v[88:91], v[164:167], v[212:215], v[88:91]
	v_mfma_f32_16x16x32_bf16 v[76:79], v[156:159], v[240:243], v[76:79]
	v_mfma_f32_16x16x32_bf16 v[72:75], v[164:167], v[240:243], v[72:75]
	s_setprio 0
	s_setprio 1
	v_mfma_f32_16x16x32_bf16 v[116:119], v[176:179], v[192:195], v[116:119]
	v_mfma_f32_16x16x32_bf16 v[112:115], v[184:187], v[192:195], v[112:115]
	v_mfma_f32_16x16x32_bf16 v[100:103], v[176:179], v[200:203], v[100:103]
	v_mfma_f32_16x16x32_bf16 v[96:99], v[184:187], v[200:203], v[96:99]
	v_mfma_f32_16x16x32_bf16 v[84:87], v[176:179], v[208:211], v[84:87]
	v_mfma_f32_16x16x32_bf16 v[80:83], v[184:187], v[208:211], v[80:83]
	v_mfma_f32_16x16x32_bf16 v[68:71], v[176:179], v[216:219], v[68:71]
	v_mfma_f32_16x16x32_bf16 v[64:67], v[184:187], v[216:219], v[64:67]
	v_mfma_f32_16x16x32_bf16 v[116:119], v[180:183], v[196:199], v[116:119]
	v_mfma_f32_16x16x32_bf16 v[112:115], v[188:191], v[196:199], v[112:115]
	v_mfma_f32_16x16x32_bf16 v[100:103], v[180:183], v[204:207], v[100:103]
	v_mfma_f32_16x16x32_bf16 v[96:99], v[188:191], v[204:207], v[96:99]
	v_mfma_f32_16x16x32_bf16 v[84:87], v[180:183], v[212:215], v[84:87]
	v_mfma_f32_16x16x32_bf16 v[80:83], v[188:191], v[212:215], v[80:83]
	v_mfma_f32_16x16x32_bf16 v[68:71], v[180:183], v[240:243], v[68:71]
	v_mfma_f32_16x16x32_bf16 v[64:67], v[188:191], v[240:243], v[64:67]
	s_setprio 0
	s_barrier
; __device__ __forceinline__ unsigned cvt_pk_bf16(float lo, float hi) { unsigned r; asm volatile("v_cvt_pk_bf16_f32 %0, %1, %2" : "=v"(r) : "v"(lo), "v"(hi)); return r; }
; __device__ __forceinline__ float gelu_tanh(float x) { const float u = 0.7978845608028654f * (x + 0.044715f * x * x * x); return x * fast_rcp(1.0f + fast_exp2(-2.0f * LOG2E * u)); }
; #define PG8_MMA(ai, bj, At, Bt) do { __builtin_amdgcn_s_setprio(1); _Pragma("unroll") for (int k = 0; k < 2; ++k) _Pragma("unroll") for (int m = 0; m < 4; ++m) _Pragma("unroll") for (int n = 0; n < 2; ++n) \
;         acc[ai][bj][m][n] = __builtin_amdgcn_mfma_f32_16x16x32_bf16(Bt[n][k], At[m][k], acc[ai][bj][m][n], 0, 0, 0); __builtin_amdgcn_s_setprio(0); } while (0)
; #define PG8_WAIT_V(n) asm volatile("s_waitcnt vmcnt(" #n ")" ::: "memory")
; #define PG8_WAIT_L(n) asm volatile("s_waitcnt lgkmcnt(" #n ")" ::: "memory")
; #define PG8_BAR __builtin_amdgcn_s_barrier()
; #define PG8_SCHED __builtin_amdgcn_sched_barrier(0)
;     __device__ __forceinline__ void operator()(const f32x4 (&acc)[2][2][4][2], const Unit& u, int wr, int wc, int fr, int fq) const {
;         const int row0 = u.pm * BM + wr * 64 + fr, col0 = u.pn * BM + wc * 32 + 8 * fq;
;         float rsv[2][4]; load_rstd(rsv, ssq, row0);
; #pragma unroll
;         for (int ai = 0; ai < 2; ++ai)
; #pragma unroll
;             for (int m = 0; m < 4; ++m) { const int row = row0 + ai * HALF + m * 16; bf16_t* rowp = O + (size_t)row * ldc + col0; const float rs = rsv[ai][m];
; #pragma unroll
;                 for (int bj = 0; bj < 2; ++bj) { f32x4 v0 = acc[ai][bj][m][0] * rs, v1 = acc[ai][bj][m][1] * rs;
;                     if (ACT == 1) {
; #pragma unroll
;                         for (int j = 0; j < 4; ++j) { v0[j] = gelu_tanh(v0[j]); v1[j] = gelu_tanh(v1[j]); } }
;                     u32x4 w; w.x = cvt_pk_bf16(v0[0], v0[1]); w.y = cvt_pk_bf16(v0[2], v0[3]); w.z = cvt_pk_bf16(v1[0], v1[1]); w.w = cvt_pk_bf16(v1[2], v1[3]);
;                     *(u32x4*)(rowp + bj * HALF) = w; } }
; template <class Epi, bool ALIGN_EPI>
; __device__ __forceinline__ void gemm_phase(LAS unsigned char* lds, const Gemm g, const StaticOrder& S, const Epi& E, const int tid) {
;     ...
;             PG8_WAIT_V(8); PG8_WAIT_L(0); PG8_BAR; PG8_MMA(1, 0, At, B0); PG8_MMA(1, 1, At, B1); PG8_BAR; PG8_SCHED;
	s_add_i32 s10, s10, s45
	v_lshl_add_u64 v[146:147], v[244:245], 0, s[92:93]
	s_mov_b32 m0, s10
	ds_read_b128 v[192:195], v151 offset:49152
	ds_read_b128 v[196:199], v151 offset:50176
	ds_read_b128 v[200:203], v151 offset:51200
	ds_read_b128 v[204:207], v151 offset:52224
	ds_read_b128 v[208:211], v151 offset:53248
	ds_read_b128 v[212:215], v151 offset:54272
	ds_read_b128 v[216:219], v151 offset:55296
	ds_read_b128 v[240:243], v151 offset:56320
	global_load_lds_dwordx4 v[146:147], off
	v_lshl_add_u64 v[146:147], v[246:247], 0, s[92:93]
	s_add_i32 m0, s10, 0x2000
	s_add_i32 s10, s62, s45
	global_load_lds_dwordx4 v[146:147], off
	v_lshl_add_u64 v[146:147], v[248:249], 0, s[92:93]
	s_mov_b32 m0, s10
	s_nop 0
	global_load_lds_dwordx4 v[146:147], off
	v_lshl_add_u64 v[146:147], v[220:221], 0, s[92:93]
	s_add_i32 m0, s10, 0x2000
	s_nop 0
	global_load_lds_dwordx4 v[146:147], off
	v_lshl_add_u64 v[146:147], v[250:251], 0, s[92:93]
	s_mov_b32 m0, s53
	s_nop 0
	global_load_lds_dwordx4 v[146:147], off
	v_lshl_add_u64 v[146:147], v[252:253], 0, s[92:93]
	s_mov_b32 m0, s54
	s_nop 0
	global_load_lds_dwordx4 v[146:147], off
	s_waitcnt vmcnt(8)
	s_waitcnt lgkmcnt(0)
	s_barrier
	s_setprio 1
	s_waitcnt lgkmcnt(0)
	v_mfma_f32_16x16x32_bf16 v[60:63], v[152:155], v[192:195], v[60:63]
	v_lshrrev_b32_e32 v171, 8, v170
	v_and_b32_e32 v234, 15, v170
	v_lshl_add_u32 v171, v171, 6, v234
	s_lshl_b32 s98, s61, 8
	v_add_u32_e32 v171, s98, v171
	v_mfma_f32_16x16x32_bf16 v[56:59], v[160:163], v[192:195], v[56:59]
	v_mul_lo_u32 v171, v171, s28
	v_bfe_u32 v234, v170, 6, 2
	v_bfe_u32 v224, v170, 4, 2
	v_lshlrev_b32_e32 v234, 5, v234
	v_lshl_or_b32 v234, v224, 3, v234
	v_mfma_f32_16x16x32_bf16 v[44:47], v[152:155], v[200:203], v[44:47]
	s_lshl_b32 s98, s60, 8
	v_add_u32_e32 v234, s98, v234
	v_add_lshl_u32 v232, v171, v234, 1
	v_mov_b32_e32 v233, 0
	v_lshl_add_u64 v[232:233], v[232:233], 0, s[30:31]
	v_mfma_f32_16x16x32_bf16 v[40:43], v[160:163], v[200:203], v[40:43]
	s_lshl_b32 s98, s28, 5
	s_mov_b32 s99, 0
	v_mul_f32_e32 v124, v172, v124
	v_mul_f32_e32 v125, v172, v125
	v_mul_f32_e32 v126, v172, v126
	v_mfma_f32_16x16x32_bf16 v[28:31], v[152:155], v[208:211], v[28:31]
	v_mul_f32_e32 v127, v172, v127
	v_mul_f32_e32 v120, v172, v120
	v_mul_f32_e32 v121, v172, v121
	v_mul_f32_e32 v122, v172, v122
	v_mul_f32_e32 v123, v172, v123
	v_mfma_f32_16x16x32_bf16 v[24:27], v[160:163], v[208:211], v[24:27]
	v_cvt_pk_bf16_f32 v124, v124, v125
	v_cvt_pk_bf16_f32 v125, v126, v127
	v_cvt_pk_bf16_f32 v126, v120, v121
	v_cvt_pk_bf16_f32 v127, v122, v123
	global_store_dwordx4 v[232:233], v[124:127], off sc1
	v_mfma_f32_16x16x32_bf16 v[12:15], v[152:155], v[216:219], v[12:15]
	v_mul_f32_e32 v116, v172, v116
	v_mul_f32_e32 v117, v172, v117
	v_mul_f32_e32 v118, v172, v118
	v_mul_f32_e32 v119, v172, v119
	v_mul_f32_e32 v112, v172, v112
	v_mfma_f32_16x16x32_bf16 v[8:11], v[160:163], v[216:219], v[8:11]
	v_mul_f32_e32 v113, v172, v113
	v_mul_f32_e32 v114, v172, v114
	v_mul_f32_e32 v115, v172, v115
	v_cvt_pk_bf16_f32 v116, v116, v117
	v_cvt_pk_bf16_f32 v117, v118, v119
	v_mfma_f32_16x16x32_bf16 v[60:63], v[156:159], v[196:199], v[60:63]
	v_cvt_pk_bf16_f32 v118, v112, v113
	v_cvt_pk_bf16_f32 v119, v114, v115
	global_store_dwordx4 v[232:233], v[116:119], off offset:256 sc1
	v_lshl_add_u64 v[232:233], v[232:233], 0, s[98:99]
	v_mul_f32_e32 v108, v173, v108
	v_mfma_f32_16x16x32_bf16 v[56:59], v[164:167], v[196:199], v[56:59]
	v_mul_f32_e32 v109, v173, v109
	v_mul_f32_e32 v110, v173, v110
	v_mul_f32_e32 v111, v173, v111
	v_mul_f32_e32 v104, v173, v104
	v_mul_f32_e32 v105, v173, v105
	v_mfma_f32_16x16x32_bf16 v[44:47], v[156:159], v[204:207], v[44:47]
	v_mul_f32_e32 v106, v173, v106
	v_mul_f32_e32 v107, v173, v107
	v_cvt_pk_bf16_f32 v108, v108, v109
	v_cvt_pk_bf16_f32 v109, v110, v111
	v_cvt_pk_bf16_f32 v110, v104, v105
	v_mfma_f32_16x16x32_bf16 v[40:43], v[164:167], v[204:207], v[40:43]
	v_cvt_pk_bf16_f32 v111, v106, v107
	global_store_dwordx4 v[232:233], v[108:111], off sc1
	v_mul_f32_e32 v100, v173, v100
	v_mul_f32_e32 v101, v173, v101
	v_mul_f32_e32 v102, v173, v102
	v_mfma_f32_16x16x32_bf16 v[28:31], v[156:159], v[212:215], v[28:31]
; __device__ __forceinline__ unsigned cvt_pk_bf16(float lo, float hi) { unsigned r; asm volatile("v_cvt_pk_bf16_f32 %0, %1, %2" : "=v"(r) : "v"(lo), "v"(hi)); return r; }
; __device__ __forceinline__ float gelu_tanh(float x) { const float u = 0.7978845608028654f * (x + 0.044715f * x * x * x); return x * fast_rcp(1.0f + fast_exp2(-2.0f * LOG2E * u)); }
; #define PG8_BAR __builtin_amdgcn_s_barrier()
;     __device__ __forceinline__ void operator()(const f32x4 (&acc)[2][2][4][2], const Unit& u, int wr, int wc, int fr, int fq) const {
;     ...
;             for (int m = 0; m < 4; ++m) { const int row = row0 + ai * HALF + m * 16; bf16_t* rowp = O + (size_t)row * ldc + col0; const float rs = rsv[ai][m];
; #pragma unroll
;                 for (int bj = 0; bj < 2; ++bj) { f32x4 v0 = acc[ai][bj][m][0] * rs, v1 = acc[ai][bj][m][1] * rs;
;                     if (ACT == 1) {
; #pragma unroll
;                         for (int j = 0; j < 4; ++j) { v0[j] = gelu_tanh(v0[j]); v1[j] = gelu_tanh(v1[j]); } }
;                     u32x4 w; w.x = cvt_pk_bf16(v0[0], v0[1]); w.y = cvt_pk_bf16(v0[2], v0[3]); w.z = cvt_pk_bf16(v1[0], v1[1]); w.w = cvt_pk_bf16(v1[2], v1[3]);
;                     *(u32x4*)(rowp + bj * HALF) = w; } }
; template <class Epi, bool ALIGN_EPI>
; __device__ __forceinline__ void gemm_phase(LAS unsigned char* lds, const Gemm g, const StaticOrder& S, const Epi& E, const int tid) {
;     ...
;         if constexpr (ALIGN_EPI) { if (wr == 0) PG8_BAR; }
;         { int t2 = tid; asm volatile("" : "+v"(t2)); const int l2 = t2 & 63, w2 = __builtin_amdgcn_readfirstlane(t2 >> 6); E(acc, cur, w2 >> 2, w2 & 3, l2 & 15, l2 >> 4); }
;         if (!has_next) break;
; #pragma unroll
;         for (int a = 0; a < 2; ++a)
; #pragma unroll
;             for (int b = 0; b < 2; ++b)
; #pragma unroll
;                 for (int m = 0; m < 4; ++m)
; #pragma unroll
;                     for (int n = 0; n < 2; ++n) acc[a][b][m][n] = (f32x4){0.f, 0.f, 0.f, 0.f};
;         cur = nxt; cA = nA; cB = nB; ++ui;
	v_mul_f32_e32 v103, v173, v103
	v_mul_f32_e32 v96, v173, v96
	v_mul_f32_e32 v97, v173, v97
	v_mul_f32_e32 v98, v173, v98
	v_mul_f32_e32 v99, v173, v99
	v_mfma_f32_16x16x32_bf16 v[24:27], v[164:167], v[212:215], v[24:27]
	v_cvt_pk_bf16_f32 v100, v100, v101
	v_cvt_pk_bf16_f32 v101, v102, v103
	v_cvt_pk_bf16_f32 v102, v96, v97
	v_cvt_pk_bf16_f32 v103, v98, v99
	global_store_dwordx4 v[232:233], v[100:103], off offset:256 sc1
	v_mfma_f32_16x16x32_bf16 v[12:15], v[156:159], v[240:243], v[12:15]
	v_lshl_add_u64 v[232:233], v[232:233], 0, s[98:99]
	v_mul_f32_e32 v92, v236, v92
	v_mul_f32_e32 v93, v236, v93
	v_mul_f32_e32 v94, v236, v94
	v_mul_f32_e32 v95, v236, v95
	v_mfma_f32_16x16x32_bf16 v[8:11], v[164:167], v[240:243], v[8:11]
	v_mul_f32_e32 v88, v236, v88
	v_mul_f32_e32 v89, v236, v89
	v_mul_f32_e32 v90, v236, v90
	v_mul_f32_e32 v91, v236, v91
	v_cvt_pk_bf16_f32 v92, v92, v93
	s_setprio 0
	s_setprio 1
	v_mfma_f32_16x16x32_bf16 v[52:55], v[176:179], v[192:195], v[52:55]
	v_cvt_pk_bf16_f32 v93, v94, v95
	v_cvt_pk_bf16_f32 v94, v88, v89
	v_cvt_pk_bf16_f32 v95, v90, v91
	global_store_dwordx4 v[232:233], v[92:95], off sc1
	v_mul_f32_e32 v84, v236, v84
	v_mfma_f32_16x16x32_bf16 v[48:51], v[184:187], v[192:195], v[48:51]
	v_mul_f32_e32 v85, v236, v85
	v_mul_f32_e32 v86, v236, v86
	v_mul_f32_e32 v87, v236, v87
	v_mul_f32_e32 v80, v236, v80
	v_mul_f32_e32 v81, v236, v81
	v_mfma_f32_16x16x32_bf16 v[36:39], v[176:179], v[200:203], v[36:39]
	v_mul_f32_e32 v82, v236, v82
	v_mul_f32_e32 v83, v236, v83
	v_cvt_pk_bf16_f32 v84, v84, v85
	v_cvt_pk_bf16_f32 v85, v86, v87
	v_cvt_pk_bf16_f32 v86, v80, v81
	v_mfma_f32_16x16x32_bf16 v[32:35], v[184:187], v[200:203], v[32:35]
	v_cvt_pk_bf16_f32 v87, v82, v83
	global_store_dwordx4 v[232:233], v[84:87], off offset:256 sc1
	v_lshl_add_u64 v[232:233], v[232:233], 0, s[98:99]
	v_mul_f32_e32 v76, v237, v76
	v_mul_f32_e32 v77, v237, v77
	v_mfma_f32_16x16x32_bf16 v[20:23], v[176:179], v[208:211], v[20:23]
	v_mul_f32_e32 v78, v237, v78
	v_mul_f32_e32 v79, v237, v79
	v_mul_f32_e32 v72, v237, v72
	v_mul_f32_e32 v73, v237, v73
	v_mul_f32_e32 v74, v237, v74
	v_mfma_f32_16x16x32_bf16 v[16:19], v[184:187], v[208:211], v[16:19]
	v_mul_f32_e32 v75, v237, v75
	v_cvt_pk_bf16_f32 v76, v76, v77
	v_cvt_pk_bf16_f32 v77, v78, v79
	v_cvt_pk_bf16_f32 v78, v72, v73
	v_cvt_pk_bf16_f32 v79, v74, v75
	v_mfma_f32_16x16x32_bf16 v[4:7], v[176:179], v[216:219], v[4:7]
	global_store_dwordx4 v[232:233], v[76:79], off sc1
	v_mul_f32_e32 v68, v237, v68
	v_mul_f32_e32 v69, v237, v69
	v_mul_f32_e32 v70, v237, v70
	v_mul_f32_e32 v71, v237, v71
	v_mfma_f32_16x16x32_bf16 v[0:3], v[184:187], v[216:219], v[0:3]
	v_mul_f32_e32 v64, v237, v64
	v_mul_f32_e32 v65, v237, v65
	v_mul_f32_e32 v66, v237, v66
	v_mul_f32_e32 v67, v237, v67
	v_cvt_pk_bf16_f32 v68, v68, v69
	v_mfma_f32_16x16x32_bf16 v[52:55], v[180:183], v[196:199], v[52:55]
	v_cvt_pk_bf16_f32 v69, v70, v71
	v_cvt_pk_bf16_f32 v70, v64, v65
	v_cvt_pk_bf16_f32 v71, v66, v67
	global_store_dwordx4 v[232:233], v[68:71], off offset:256 sc1
	v_lshl_add_u64 v[232:233], v[232:233], 0, s[98:99]
	v_mfma_f32_16x16x32_bf16 v[48:51], v[188:191], v[196:199], v[48:51]
	v_lshl_add_u64 v[232:233], v[232:233], 0, s[98:99]
	v_lshl_add_u64 v[232:233], v[232:233], 0, s[98:99]
	v_lshl_add_u64 v[232:233], v[232:233], 0, s[98:99]
	v_lshl_add_u64 v[232:233], v[232:233], 0, s[98:99]
	v_mfma_f32_16x16x32_bf16 v[36:39], v[180:183], v[204:207], v[36:39]
	v_mfma_f32_16x16x32_bf16 v[32:35], v[188:191], v[204:207], v[32:35]
	v_mfma_f32_16x16x32_bf16 v[20:23], v[180:183], v[212:215], v[20:23]
	v_mfma_f32_16x16x32_bf16 v[16:19], v[188:191], v[212:215], v[16:19]
	v_mfma_f32_16x16x32_bf16 v[4:7], v[180:183], v[240:243], v[4:7]
	v_mfma_f32_16x16x32_bf16 v[0:3], v[188:191], v[240:243], v[0:3]
	s_setprio 0
	s_barrier
	v_lshl_add_u64 v[142:143], v[142:143], 0, s[80:81]
	v_lshl_add_u64 v[144:145], v[144:145], 0, s[80:81]
	s_and_b64 vcc, exec, s[8:9]
	s_cbranch_vccnz .Lq5_notdefer
	s_cmp_lg_u32 s59, s61
	s_cbranch_scc1 .Lq5_notdefer
	s_mov_b32 s101, 1
	s_mov_b32 s60, s58
	s_mov_b32 s61, s59
	v_mov_b64_e32 v[144:145], v[140:141]
	v_mov_b64_e32 v[142:143], v[138:139]
	s_branch .LBB0_346

; __device__ __forceinline__ unsigned cvt_pk_bf16(float lo, float hi) { unsigned r; asm volatile("v_cvt_pk_bf16_f32 %0, %1, %2" : "=v"(r) : "v"(lo), "v"(hi)); return r; }
; __device__ __forceinline__ float gelu_tanh(float x) { const float u = 0.7978845608028654f * (x + 0.044715f * x * x * x); return x * fast_rcp(1.0f + fast_exp2(-2.0f * LOG2E * u)); }
; #define PG8_BAR __builtin_amdgcn_s_barrier()
;     __device__ __forceinline__ void operator()(const f32x4 (&acc)[2][2][4][2], const Unit& u, int wr, int wc, int fr, int fq) const {
;     ...
;             for (int m = 0; m < 4; ++m) { const int row = row0 + ai * HALF + m * 16; bf16_t* rowp = O + (size_t)row * ldc + col0; const float rs = rsv[ai][m];
; #pragma unroll
;                 for (int bj = 0; bj < 2; ++bj) { f32x4 v0 = acc[ai][bj][m][0] * rs, v1 = acc[ai][bj][m][1] * rs;
;                     if (ACT == 1) {
; #pragma unroll
;                         for (int j = 0; j < 4; ++j) { v0[j] = gelu_tanh(v0[j]); v1[j] = gelu_tanh(v1[j]); } }
;                     u32x4 w; w.x = cvt_pk_bf16(v0[0], v0[1]); w.y = cvt_pk_bf16(v0[2], v0[3]); w.z = cvt_pk_bf16(v1[0], v1[1]); w.w = cvt_pk_bf16(v1[2], v1[3]);
;                     *(u32x4*)(rowp + bj * HALF) = w; } }
; template <class Epi, bool ALIGN_EPI>
; __device__ __forceinline__ void gemm_phase(LAS unsigned char* lds, const Gemm g, const StaticOrder& S, const Epi& E, const int tid) {
;     ...
;         if constexpr (ALIGN_EPI) { if (wr == 0) PG8_BAR; }
;         { int t2 = tid; asm volatile("" : "+v"(t2)); const int l2 = t2 & 63, w2 = __builtin_amdgcn_readfirstlane(t2 >> 6); E(acc, cur, w2 >> 2, w2 & 3, l2 & 15, l2 >> 4); }
;         if (!has_next) break;
.Lq5_nopf:
	s_lshl_b32 s98, s28, 5
	s_mov_b32 s99, 0
	v_pk_mul_f32 v[60:61], v[60:61], v[238:239] op_sel_hi:[1,0]
	v_pk_mul_f32 v[62:63], v[62:63], v[238:239] op_sel_hi:[1,0]
	v_pk_mul_f32 v[56:57], v[56:57], v[238:239] op_sel_hi:[1,0]
	v_pk_mul_f32 v[58:59], v[58:59], v[238:239] op_sel_hi:[1,0]
	v_cvt_pk_bf16_f32 v60, v60, v61
	v_cvt_pk_bf16_f32 v61, v62, v63
	v_cvt_pk_bf16_f32 v62, v56, v57
	v_cvt_pk_bf16_f32 v63, v58, v59
	global_store_dwordx4 v[232:233], v[60:63], off sc1
	v_pk_mul_f32 v[52:53], v[52:53], v[238:239] op_sel_hi:[1,0]
	v_pk_mul_f32 v[54:55], v[54:55], v[238:239] op_sel_hi:[1,0]
	v_pk_mul_f32 v[48:49], v[48:49], v[238:239] op_sel_hi:[1,0]
	v_pk_mul_f32 v[50:51], v[50:51], v[238:239] op_sel_hi:[1,0]
	v_cvt_pk_bf16_f32 v52, v52, v53
	v_cvt_pk_bf16_f32 v53, v54, v55
	v_cvt_pk_bf16_f32 v54, v48, v49
	v_cvt_pk_bf16_f32 v55, v50, v51
	global_store_dwordx4 v[232:233], v[52:55], off offset:256 sc1
	v_lshl_add_u64 v[232:233], v[232:233], 0, s[98:99]
	v_pk_mul_f32 v[44:45], v[44:45], v[238:239] op_sel:[0,1]
	v_pk_mul_f32 v[46:47], v[46:47], v[238:239] op_sel:[0,1]
	v_pk_mul_f32 v[40:41], v[40:41], v[238:239] op_sel:[0,1]
	v_pk_mul_f32 v[42:43], v[42:43], v[238:239] op_sel:[0,1]
	v_cvt_pk_bf16_f32 v44, v44, v45
	v_cvt_pk_bf16_f32 v45, v46, v47
	v_cvt_pk_bf16_f32 v46, v40, v41
	v_cvt_pk_bf16_f32 v47, v42, v43
	global_store_dwordx4 v[232:233], v[44:47], off sc1
	v_pk_mul_f32 v[36:37], v[36:37], v[238:239] op_sel:[0,1]
	v_pk_mul_f32 v[38:39], v[38:39], v[238:239] op_sel:[0,1]
	v_pk_mul_f32 v[32:33], v[32:33], v[238:239] op_sel:[0,1]
	v_pk_mul_f32 v[34:35], v[34:35], v[238:239] op_sel:[0,1]
	v_cvt_pk_bf16_f32 v36, v36, v37
	v_cvt_pk_bf16_f32 v37, v38, v39
	v_cvt_pk_bf16_f32 v38, v32, v33
	v_cvt_pk_bf16_f32 v39, v34, v35
	global_store_dwordx4 v[232:233], v[36:39], off offset:256 sc1
	v_lshl_add_u64 v[232:233], v[232:233], 0, s[98:99]
	v_pk_mul_f32 v[28:29], v[28:29], v[230:231] op_sel_hi:[1,0]
	v_pk_mul_f32 v[30:31], v[30:31], v[230:231] op_sel_hi:[1,0]
	v_pk_mul_f32 v[24:25], v[24:25], v[230:231] op_sel_hi:[1,0]
	v_pk_mul_f32 v[26:27], v[26:27], v[230:231] op_sel_hi:[1,0]
	v_cvt_pk_bf16_f32 v28, v28, v29
	v_cvt_pk_bf16_f32 v29, v30, v31
	v_cvt_pk_bf16_f32 v30, v24, v25
	v_cvt_pk_bf16_f32 v31, v26, v27
	global_store_dwordx4 v[232:233], v[28:31], off sc1
	v_pk_mul_f32 v[20:21], v[20:21], v[230:231] op_sel_hi:[1,0]
	v_pk_mul_f32 v[22:23], v[22:23], v[230:231] op_sel_hi:[1,0]
	v_pk_mul_f32 v[16:17], v[16:17], v[230:231] op_sel_hi:[1,0]
	v_pk_mul_f32 v[18:19], v[18:19], v[230:231] op_sel_hi:[1,0]
	v_cvt_pk_bf16_f32 v20, v20, v21
	v_cvt_pk_bf16_f32 v21, v22, v23
	v_cvt_pk_bf16_f32 v22, v16, v17
	v_cvt_pk_bf16_f32 v23, v18, v19
	global_store_dwordx4 v[232:233], v[20:23], off offset:256 sc1
	v_lshl_add_u64 v[232:233], v[232:233], 0, s[98:99]
	v_pk_mul_f32 v[12:13], v[12:13], v[230:231] op_sel:[0,1]
	v_pk_mul_f32 v[14:15], v[14:15], v[230:231] op_sel:[0,1]
	v_pk_mul_f32 v[8:9], v[8:9], v[230:231] op_sel:[0,1]
	v_pk_mul_f32 v[10:11], v[10:11], v[230:231] op_sel:[0,1]
	v_cvt_pk_bf16_f32 v12, v12, v13
	v_cvt_pk_bf16_f32 v13, v14, v15
	v_cvt_pk_bf16_f32 v14, v8, v9
	v_cvt_pk_bf16_f32 v15, v10, v11
	global_store_dwordx4 v[232:233], v[12:15], off sc1
	v_pk_mul_f32 v[4:5], v[4:5], v[230:231] op_sel:[0,1]
	v_pk_mul_f32 v[6:7], v[6:7], v[230:231] op_sel:[0,1]
	v_pk_mul_f32 v[0:1], v[0:1], v[230:231] op_sel:[0,1]
	v_pk_mul_f32 v[2:3], v[2:3], v[230:231] op_sel:[0,1]
	v_cvt_pk_bf16_f32 v4, v4, v5
	v_cvt_pk_bf16_f32 v5, v6, v7
	v_cvt_pk_bf16_f32 v6, v0, v1
	v_cvt_pk_bf16_f32 v7, v2, v3
	global_store_dwordx4 v[232:233], v[4:7], off offset:256 sc1
	s_mov_b32 s101, 0
	s_mov_b64 s[10:11], -1
	s_and_b64 vcc, exec, s[8:9]
	s_cbranch_vccnz .LBB0_345
	s_andn2_b64 vcc, exec, s[40:41]
	s_cbranch_vccnz .LBB0_344
	s_barrier
	s_branch .LBB0_344
